# mlp1 (squared-ReLU) tile end: U tile transposed through LDS, stored as row-contiguous dwordx4 write-through (sc1); stage-2 prefetch issued after
# speedup vs baseline: 1.0091x; 1.0043x over previous
.LBB0_80:
	v_readfirstlane_b32 s6, v137
	s_lshr_b32 s6, s6, 6
	s_and_b32 s14, s6, 1
	s_lshr_b32 s19, s6, 1
	s_lshl_b32 s19, s19, 6
	s_add_i32 s19, s19, s26
	s_lshl_b32 s14, s14, 6
	s_add_i32 s14, s14, s22
	s_lshl_b32 s6, s6, 12
	s_add_i32 s6, s6, 0x18000
	v_and_b32_e32 v202, 63, v137
	v_and_b32_e32 v203, 15, v202
	v_lshrrev_b32_e32 v204, 4, v202
	v_and_b32_e32 v205, 3, v203
	v_lshrrev_b32_e32 v206, 2, v203
	v_lshl_or_b32 v207, v204, 2, v205
	s_mov_b32 s36, 0xaaaaaaaa
	s_mov_b32 s37, 0xaaaaaaaa
	s_mov_b32 s50, 0xcccccccc
	s_mov_b32 s51, 0xcccccccc
	v_and_b32_e32 v208, 7, v207
	v_lshlrev_b32_e32 v208, 1, v208
	v_or_b32_e32 v209, 0, v206
	v_xor_b32_e32 v209, v209, v208
	v_lshlrev_b32_e32 v209, 3, v209
	v_lshl_add_u32 v209, v207, 7, v209
	v_add_u32_e32 v209, s6, v209
	v_or_b32_e32 v210, 4, v206
	v_xor_b32_e32 v210, v210, v208
	v_lshlrev_b32_e32 v210, 3, v210
	v_lshl_add_u32 v210, v207, 7, v210
	v_add_u32_e32 v210, s6, v210
	v_or_b32_e32 v211, 8, v206
	v_xor_b32_e32 v211, v211, v208
	v_lshlrev_b32_e32 v211, 3, v211
	v_lshl_add_u32 v211, v207, 7, v211
	v_add_u32_e32 v211, s6, v211
	v_or_b32_e32 v212, 12, v206
	v_xor_b32_e32 v212, v212, v208
	v_lshlrev_b32_e32 v212, 3, v212
	v_lshl_add_u32 v212, v207, 7, v212
	v_add_u32_e32 v212, s6, v212
	v_lshl_add_u32 v213, v202, 4, s6
	v_lshrrev_b32_e32 v214, 3, v202
	v_and_b32_e32 v215, 7, v202
	v_xor_b32_e32 v215, v215, v214
	v_add_u32_e32 v214, s19, v214
	v_lshlrev_b32_e32 v214, 13, v214
	v_lshl_add_u32 v214, v215, 4, v214
	s_lshl_b32 s27, s14, 1
	v_add_u32_e32 v214, s27, v214
	s_add_u32 s16, s94, 0xe1d8000
	s_addc_u32 s17, s95, 0
	v_max_f32_e32 v62, 0, v62
	v_max_f32_e32 v63, 0, v63
	v_max_f32_e32 v64, 0, v64
	v_max_f32_e32 v65, 0, v65
	v_mul_f32_e32 v62, v62, v62
	v_mul_f32_e32 v63, v63, v63
	v_mul_f32_e32 v64, v64, v64
	v_mul_f32_e32 v65, v65, v65
	v_max_f32_e32 v58, 0, v58
	v_max_f32_e32 v59, 0, v59
	v_max_f32_e32 v60, 0, v60
	v_max_f32_e32 v61, 0, v61
	v_mul_f32_e32 v58, v58, v58
	v_mul_f32_e32 v59, v59, v59
	v_mul_f32_e32 v60, v60, v60
	v_mul_f32_e32 v61, v61, v61
	v_max_f32_e32 v54, 0, v54
	v_max_f32_e32 v55, 0, v55
	v_max_f32_e32 v56, 0, v56
	v_max_f32_e32 v57, 0, v57
	v_mul_f32_e32 v54, v54, v54
	v_mul_f32_e32 v55, v55, v55
	v_mul_f32_e32 v56, v56, v56
	v_mul_f32_e32 v57, v57, v57
	v_max_f32_e32 v50, 0, v50
	v_max_f32_e32 v51, 0, v51
	v_max_f32_e32 v52, 0, v52
	v_max_f32_e32 v53, 0, v53
	v_mul_f32_e32 v50, v50, v50
	v_mul_f32_e32 v51, v51, v51
	v_mul_f32_e32 v52, v52, v52
	v_mul_f32_e32 v53, v53, v53
	v_max_f32_e32 v46, 0, v46
	v_max_f32_e32 v47, 0, v47
	v_max_f32_e32 v48, 0, v48
	v_max_f32_e32 v49, 0, v49
	v_mul_f32_e32 v46, v46, v46
	v_mul_f32_e32 v47, v47, v47
	v_mul_f32_e32 v48, v48, v48
	v_mul_f32_e32 v49, v49, v49
	v_max_f32_e32 v42, 0, v42
	v_max_f32_e32 v43, 0, v43
	v_max_f32_e32 v44, 0, v44
	v_max_f32_e32 v45, 0, v45
	v_mul_f32_e32 v42, v42, v42
	v_mul_f32_e32 v43, v43, v43
	v_mul_f32_e32 v44, v44, v44
	v_mul_f32_e32 v45, v45, v45
	v_max_f32_e32 v38, 0, v38
	v_max_f32_e32 v39, 0, v39
	v_max_f32_e32 v40, 0, v40
	v_max_f32_e32 v41, 0, v41
	v_mul_f32_e32 v38, v38, v38
	v_mul_f32_e32 v39, v39, v39
	v_mul_f32_e32 v40, v40, v40
	v_mul_f32_e32 v41, v41, v41
	v_max_f32_e32 v34, 0, v34
	v_max_f32_e32 v35, 0, v35
	v_max_f32_e32 v36, 0, v36
	v_max_f32_e32 v37, 0, v37
	v_mul_f32_e32 v34, v34, v34
	v_mul_f32_e32 v35, v35, v35
	v_mul_f32_e32 v36, v36, v36
	v_mul_f32_e32 v37, v37, v37
	s_nop 1
	v_mov_b32_dpp v72, v63 quad_perm:[1,0,3,2] row_mask:0xf bank_mask:0xf
	v_mov_b32_dpp v73, v62 quad_perm:[1,0,3,2] row_mask:0xf bank_mask:0xf
	v_mov_b32_dpp v74, v65 quad_perm:[1,0,3,2] row_mask:0xf bank_mask:0xf
	v_mov_b32_dpp v75, v64 quad_perm:[1,0,3,2] row_mask:0xf bank_mask:0xf
	v_cndmask_b32_e64 v62, v62, v72, s[36:37]
	v_cndmask_b32_e64 v63, v73, v63, s[36:37]
	v_cndmask_b32_e64 v64, v64, v74, s[36:37]
	v_cndmask_b32_e64 v65, v75, v65, s[36:37]
	s_nop 1
	v_mov_b32_dpp v74, v62 quad_perm:[2,3,0,1] row_mask:0xf bank_mask:0xf
	v_mov_b32_dpp v75, v63 quad_perm:[2,3,0,1] row_mask:0xf bank_mask:0xf
	v_mov_b32_dpp v72, v64 quad_perm:[2,3,0,1] row_mask:0xf bank_mask:0xf
	v_mov_b32_dpp v73, v65 quad_perm:[2,3,0,1] row_mask:0xf bank_mask:0xf
	v_cndmask_b32_e64 v62, v62, v72, s[50:51]
	v_cndmask_b32_e64 v63, v63, v73, s[50:51]
	v_cndmask_b32_e64 v64, v74, v64, s[50:51]
	v_cndmask_b32_e64 v65, v75, v65, s[50:51]
	s_nop 1
	v_mov_b32_dpp v72, v59 quad_perm:[1,0,3,2] row_mask:0xf bank_mask:0xf
	v_mov_b32_dpp v73, v58 quad_perm:[1,0,3,2] row_mask:0xf bank_mask:0xf
	v_mov_b32_dpp v74, v61 quad_perm:[1,0,3,2] row_mask:0xf bank_mask:0xf
	v_mov_b32_dpp v75, v60 quad_perm:[1,0,3,2] row_mask:0xf bank_mask:0xf
	v_cndmask_b32_e64 v58, v58, v72, s[36:37]
	v_cndmask_b32_e64 v59, v73, v59, s[36:37]
	v_cndmask_b32_e64 v60, v60, v74, s[36:37]
	v_cndmask_b32_e64 v61, v75, v61, s[36:37]
	s_nop 1
	v_mov_b32_dpp v74, v58 quad_perm:[2,3,0,1] row_mask:0xf bank_mask:0xf
	v_mov_b32_dpp v75, v59 quad_perm:[2,3,0,1] row_mask:0xf bank_mask:0xf
	v_mov_b32_dpp v72, v60 quad_perm:[2,3,0,1] row_mask:0xf bank_mask:0xf
	v_mov_b32_dpp v73, v61 quad_perm:[2,3,0,1] row_mask:0xf bank_mask:0xf
	v_cndmask_b32_e64 v58, v58, v72, s[50:51]
	v_cndmask_b32_e64 v59, v59, v73, s[50:51]
	v_cndmask_b32_e64 v60, v74, v60, s[50:51]
	v_cndmask_b32_e64 v61, v75, v61, s[50:51]
	s_nop 1
	v_mov_b32_dpp v72, v55 quad_perm:[1,0,3,2] row_mask:0xf bank_mask:0xf
	v_mov_b32_dpp v73, v54 quad_perm:[1,0,3,2] row_mask:0xf bank_mask:0xf
	v_mov_b32_dpp v74, v57 quad_perm:[1,0,3,2] row_mask:0xf bank_mask:0xf
	v_mov_b32_dpp v75, v56 quad_perm:[1,0,3,2] row_mask:0xf bank_mask:0xf
	v_cndmask_b32_e64 v54, v54, v72, s[36:37]
	v_cndmask_b32_e64 v55, v73, v55, s[36:37]
	v_cndmask_b32_e64 v56, v56, v74, s[36:37]
	v_cndmask_b32_e64 v57, v75, v57, s[36:37]
	s_nop 1
	v_mov_b32_dpp v74, v54 quad_perm:[2,3,0,1] row_mask:0xf bank_mask:0xf
	v_mov_b32_dpp v75, v55 quad_perm:[2,3,0,1] row_mask:0xf bank_mask:0xf
	v_mov_b32_dpp v72, v56 quad_perm:[2,3,0,1] row_mask:0xf bank_mask:0xf
	v_mov_b32_dpp v73, v57 quad_perm:[2,3,0,1] row_mask:0xf bank_mask:0xf
	v_cndmask_b32_e64 v54, v54, v72, s[50:51]
	v_cndmask_b32_e64 v55, v55, v73, s[50:51]
	v_cndmask_b32_e64 v56, v74, v56, s[50:51]
	v_cndmask_b32_e64 v57, v75, v57, s[50:51]
	s_nop 1
	v_mov_b32_dpp v72, v51 quad_perm:[1,0,3,2] row_mask:0xf bank_mask:0xf
	v_mov_b32_dpp v73, v50 quad_perm:[1,0,3,2] row_mask:0xf bank_mask:0xf
	v_mov_b32_dpp v74, v53 quad_perm:[1,0,3,2] row_mask:0xf bank_mask:0xf
	v_mov_b32_dpp v75, v52 quad_perm:[1,0,3,2] row_mask:0xf bank_mask:0xf
	v_cndmask_b32_e64 v50, v50, v72, s[36:37]
	v_cndmask_b32_e64 v51, v73, v51, s[36:37]
	v_cndmask_b32_e64 v52, v52, v74, s[36:37]
	v_cndmask_b32_e64 v53, v75, v53, s[36:37]
	s_nop 1
	v_mov_b32_dpp v74, v50 quad_perm:[2,3,0,1] row_mask:0xf bank_mask:0xf
	v_mov_b32_dpp v75, v51 quad_perm:[2,3,0,1] row_mask:0xf bank_mask:0xf
	v_mov_b32_dpp v72, v52 quad_perm:[2,3,0,1] row_mask:0xf bank_mask:0xf
	v_mov_b32_dpp v73, v53 quad_perm:[2,3,0,1] row_mask:0xf bank_mask:0xf
	v_cndmask_b32_e64 v50, v50, v72, s[50:51]
	v_cndmask_b32_e64 v51, v51, v73, s[50:51]
	v_cndmask_b32_e64 v52, v74, v52, s[50:51]
	v_cndmask_b32_e64 v53, v75, v53, s[50:51]
	s_nop 1
	v_mov_b32_dpp v72, v47 quad_perm:[1,0,3,2] row_mask:0xf bank_mask:0xf
	v_mov_b32_dpp v73, v46 quad_perm:[1,0,3,2] row_mask:0xf bank_mask:0xf
	v_mov_b32_dpp v74, v49 quad_perm:[1,0,3,2] row_mask:0xf bank_mask:0xf
	v_mov_b32_dpp v75, v48 quad_perm:[1,0,3,2] row_mask:0xf bank_mask:0xf
	v_cndmask_b32_e64 v46, v46, v72, s[36:37]
	v_cndmask_b32_e64 v47, v73, v47, s[36:37]
	v_cndmask_b32_e64 v48, v48, v74, s[36:37]
	v_cndmask_b32_e64 v49, v75, v49, s[36:37]
	s_nop 1
	v_mov_b32_dpp v74, v46 quad_perm:[2,3,0,1] row_mask:0xf bank_mask:0xf
	v_mov_b32_dpp v75, v47 quad_perm:[2,3,0,1] row_mask:0xf bank_mask:0xf
	v_mov_b32_dpp v72, v48 quad_perm:[2,3,0,1] row_mask:0xf bank_mask:0xf
	v_mov_b32_dpp v73, v49 quad_perm:[2,3,0,1] row_mask:0xf bank_mask:0xf
	v_cndmask_b32_e64 v46, v46, v72, s[50:51]
	v_cndmask_b32_e64 v47, v47, v73, s[50:51]
	v_cndmask_b32_e64 v48, v74, v48, s[50:51]
	v_cndmask_b32_e64 v49, v75, v49, s[50:51]
	s_nop 1
	v_mov_b32_dpp v72, v43 quad_perm:[1,0,3,2] row_mask:0xf bank_mask:0xf
	v_mov_b32_dpp v73, v42 quad_perm:[1,0,3,2] row_mask:0xf bank_mask:0xf
	v_mov_b32_dpp v74, v45 quad_perm:[1,0,3,2] row_mask:0xf bank_mask:0xf
	v_mov_b32_dpp v75, v44 quad_perm:[1,0,3,2] row_mask:0xf bank_mask:0xf
	v_cndmask_b32_e64 v42, v42, v72, s[36:37]
	v_cndmask_b32_e64 v43, v73, v43, s[36:37]
	v_cndmask_b32_e64 v44, v44, v74, s[36:37]
	v_cndmask_b32_e64 v45, v75, v45, s[36:37]
	s_nop 1
	v_mov_b32_dpp v74, v42 quad_perm:[2,3,0,1] row_mask:0xf bank_mask:0xf
	v_mov_b32_dpp v75, v43 quad_perm:[2,3,0,1] row_mask:0xf bank_mask:0xf
	v_mov_b32_dpp v72, v44 quad_perm:[2,3,0,1] row_mask:0xf bank_mask:0xf
	v_mov_b32_dpp v73, v45 quad_perm:[2,3,0,1] row_mask:0xf bank_mask:0xf
	v_cndmask_b32_e64 v42, v42, v72, s[50:51]
	v_cndmask_b32_e64 v43, v43, v73, s[50:51]
	v_cndmask_b32_e64 v44, v74, v44, s[50:51]
	v_cndmask_b32_e64 v45, v75, v45, s[50:51]
	s_nop 1
	v_mov_b32_dpp v72, v39 quad_perm:[1,0,3,2] row_mask:0xf bank_mask:0xf
	v_mov_b32_dpp v73, v38 quad_perm:[1,0,3,2] row_mask:0xf bank_mask:0xf
	v_mov_b32_dpp v74, v41 quad_perm:[1,0,3,2] row_mask:0xf bank_mask:0xf
	v_mov_b32_dpp v75, v40 quad_perm:[1,0,3,2] row_mask:0xf bank_mask:0xf
	v_cndmask_b32_e64 v38, v38, v72, s[36:37]
	v_cndmask_b32_e64 v39, v73, v39, s[36:37]
	v_cndmask_b32_e64 v40, v40, v74, s[36:37]
	v_cndmask_b32_e64 v41, v75, v41, s[36:37]
	s_nop 1
	v_mov_b32_dpp v74, v38 quad_perm:[2,3,0,1] row_mask:0xf bank_mask:0xf
	v_mov_b32_dpp v75, v39 quad_perm:[2,3,0,1] row_mask:0xf bank_mask:0xf
	v_mov_b32_dpp v72, v40 quad_perm:[2,3,0,1] row_mask:0xf bank_mask:0xf
	v_mov_b32_dpp v73, v41 quad_perm:[2,3,0,1] row_mask:0xf bank_mask:0xf
	v_cndmask_b32_e64 v38, v38, v72, s[50:51]
	v_cndmask_b32_e64 v39, v39, v73, s[50:51]
	v_cndmask_b32_e64 v40, v74, v40, s[50:51]
	v_cndmask_b32_e64 v41, v75, v41, s[50:51]
	s_nop 1
	v_mov_b32_dpp v72, v35 quad_perm:[1,0,3,2] row_mask:0xf bank_mask:0xf
	v_mov_b32_dpp v73, v34 quad_perm:[1,0,3,2] row_mask:0xf bank_mask:0xf
	v_mov_b32_dpp v74, v37 quad_perm:[1,0,3,2] row_mask:0xf bank_mask:0xf
	v_mov_b32_dpp v75, v36 quad_perm:[1,0,3,2] row_mask:0xf bank_mask:0xf
	v_cndmask_b32_e64 v34, v34, v72, s[36:37]
	v_cndmask_b32_e64 v35, v73, v35, s[36:37]
	v_cndmask_b32_e64 v36, v36, v74, s[36:37]
	v_cndmask_b32_e64 v37, v75, v37, s[36:37]
	s_nop 1
	v_mov_b32_dpp v74, v34 quad_perm:[2,3,0,1] row_mask:0xf bank_mask:0xf
	v_mov_b32_dpp v75, v35 quad_perm:[2,3,0,1] row_mask:0xf bank_mask:0xf
	v_mov_b32_dpp v72, v36 quad_perm:[2,3,0,1] row_mask:0xf bank_mask:0xf
	v_mov_b32_dpp v73, v37 quad_perm:[2,3,0,1] row_mask:0xf bank_mask:0xf
	v_cndmask_b32_e64 v34, v34, v72, s[50:51]
	v_cndmask_b32_e64 v35, v35, v73, s[50:51]
	v_cndmask_b32_e64 v36, v74, v36, s[50:51]
	v_cndmask_b32_e64 v37, v75, v37, s[50:51]
	v_cvt_pk_bf16_f32 v62, v62, v63
	v_cvt_pk_bf16_f32 v63, v64, v65
	ds_write_b64 v209, v[62:63] offset:0
	v_cvt_pk_bf16_f32 v58, v58, v59
	v_cvt_pk_bf16_f32 v59, v60, v61
	ds_write_b64 v210, v[58:59] offset:0
	v_cvt_pk_bf16_f32 v54, v54, v55
	v_cvt_pk_bf16_f32 v55, v56, v57
	ds_write_b64 v211, v[54:55] offset:0
	v_cvt_pk_bf16_f32 v50, v50, v51
	v_cvt_pk_bf16_f32 v51, v52, v53
	ds_write_b64 v212, v[50:51] offset:0
	v_cvt_pk_bf16_f32 v46, v46, v47
	v_cvt_pk_bf16_f32 v47, v48, v49
	ds_write_b64 v209, v[46:47] offset:2048
	v_cvt_pk_bf16_f32 v42, v42, v43
	v_cvt_pk_bf16_f32 v43, v44, v45
	ds_write_b64 v210, v[42:43] offset:2048
	v_cvt_pk_bf16_f32 v38, v38, v39
	v_cvt_pk_bf16_f32 v39, v40, v41
	ds_write_b64 v211, v[38:39] offset:2048
	v_cvt_pk_bf16_f32 v34, v34, v35
	v_cvt_pk_bf16_f32 v35, v36, v37
	ds_write_b64 v212, v[34:35] offset:2048
	s_waitcnt lgkmcnt(0)
	ds_read_b128 v[76:79], v213 offset:0
	ds_read_b128 v[80:83], v213 offset:1024
	ds_read_b128 v[84:87], v213 offset:2048
	ds_read_b128 v[88:91], v213 offset:3072
	s_waitcnt lgkmcnt(3)
	global_store_dwordx4 v214, v[76:79], s[16:17] sc1
	s_waitcnt lgkmcnt(2)
	v_add_u32_e32 v216, 0x10000, v214
	global_store_dwordx4 v216, v[80:83], s[16:17] sc1
	s_waitcnt lgkmcnt(1)
	v_add_u32_e32 v216, 0x20000, v214
	global_store_dwordx4 v216, v[84:87], s[16:17] sc1
	s_waitcnt lgkmcnt(0)
	v_add_u32_e32 v216, 0x30000, v214
	global_store_dwordx4 v216, v[88:91], s[16:17] sc1
	s_nop 1
	v_max_f32_e32 v30, 0, v30
	v_max_f32_e32 v31, 0, v31
	v_max_f32_e32 v32, 0, v32
	v_max_f32_e32 v33, 0, v33
	v_mul_f32_e32 v30, v30, v30
	v_mul_f32_e32 v31, v31, v31
	v_mul_f32_e32 v32, v32, v32
	v_mul_f32_e32 v33, v33, v33
	v_max_f32_e32 v26, 0, v26
	v_max_f32_e32 v27, 0, v27
	v_max_f32_e32 v28, 0, v28
	v_max_f32_e32 v29, 0, v29
	v_mul_f32_e32 v26, v26, v26
	v_mul_f32_e32 v27, v27, v27
	v_mul_f32_e32 v28, v28, v28
	v_mul_f32_e32 v29, v29, v29
	v_max_f32_e32 v22, 0, v22
	v_max_f32_e32 v23, 0, v23
	v_max_f32_e32 v24, 0, v24
	v_max_f32_e32 v25, 0, v25
	v_mul_f32_e32 v22, v22, v22
	v_mul_f32_e32 v23, v23, v23
	v_mul_f32_e32 v24, v24, v24
	v_mul_f32_e32 v25, v25, v25
	v_max_f32_e32 v18, 0, v18
	v_max_f32_e32 v19, 0, v19
	v_max_f32_e32 v20, 0, v20
	v_max_f32_e32 v21, 0, v21
	v_mul_f32_e32 v18, v18, v18
	v_mul_f32_e32 v19, v19, v19
	v_mul_f32_e32 v20, v20, v20
	v_mul_f32_e32 v21, v21, v21
	v_max_f32_e32 v14, 0, v14
	v_max_f32_e32 v15, 0, v15
	v_max_f32_e32 v16, 0, v16
	v_max_f32_e32 v17, 0, v17
	v_mul_f32_e32 v14, v14, v14
	v_mul_f32_e32 v15, v15, v15
	v_mul_f32_e32 v16, v16, v16
	v_mul_f32_e32 v17, v17, v17
	v_max_f32_e32 v10, 0, v10
	v_max_f32_e32 v11, 0, v11
	v_max_f32_e32 v12, 0, v12
	v_max_f32_e32 v13, 0, v13
	v_mul_f32_e32 v10, v10, v10
	v_mul_f32_e32 v11, v11, v11
	v_mul_f32_e32 v12, v12, v12
	v_mul_f32_e32 v13, v13, v13
	v_max_f32_e32 v6, 0, v6
	v_max_f32_e32 v7, 0, v7
	v_max_f32_e32 v8, 0, v8
	v_max_f32_e32 v9, 0, v9
	v_mul_f32_e32 v6, v6, v6
	v_mul_f32_e32 v7, v7, v7
	v_mul_f32_e32 v8, v8, v8
	v_mul_f32_e32 v9, v9, v9
	v_max_f32_e32 v2, 0, v2
	v_max_f32_e32 v3, 0, v3
	v_max_f32_e32 v4, 0, v4
	v_max_f32_e32 v5, 0, v5
	v_mul_f32_e32 v2, v2, v2
	v_mul_f32_e32 v3, v3, v3
	v_mul_f32_e32 v4, v4, v4
	v_mul_f32_e32 v5, v5, v5
	s_nop 1
	v_mov_b32_dpp v72, v31 quad_perm:[1,0,3,2] row_mask:0xf bank_mask:0xf
	v_mov_b32_dpp v73, v30 quad_perm:[1,0,3,2] row_mask:0xf bank_mask:0xf
	v_mov_b32_dpp v74, v33 quad_perm:[1,0,3,2] row_mask:0xf bank_mask:0xf
	v_mov_b32_dpp v75, v32 quad_perm:[1,0,3,2] row_mask:0xf bank_mask:0xf
	v_cndmask_b32_e64 v30, v30, v72, s[36:37]
	v_cndmask_b32_e64 v31, v73, v31, s[36:37]
	v_cndmask_b32_e64 v32, v32, v74, s[36:37]
	v_cndmask_b32_e64 v33, v75, v33, s[36:37]
	s_nop 1
	v_mov_b32_dpp v74, v30 quad_perm:[2,3,0,1] row_mask:0xf bank_mask:0xf
	v_mov_b32_dpp v75, v31 quad_perm:[2,3,0,1] row_mask:0xf bank_mask:0xf
	v_mov_b32_dpp v72, v32 quad_perm:[2,3,0,1] row_mask:0xf bank_mask:0xf
	v_mov_b32_dpp v73, v33 quad_perm:[2,3,0,1] row_mask:0xf bank_mask:0xf
	v_cndmask_b32_e64 v30, v30, v72, s[50:51]
	v_cndmask_b32_e64 v31, v31, v73, s[50:51]
	v_cndmask_b32_e64 v32, v74, v32, s[50:51]
	v_cndmask_b32_e64 v33, v75, v33, s[50:51]
	s_nop 1
	v_mov_b32_dpp v72, v27 quad_perm:[1,0,3,2] row_mask:0xf bank_mask:0xf
	v_mov_b32_dpp v73, v26 quad_perm:[1,0,3,2] row_mask:0xf bank_mask:0xf
	v_mov_b32_dpp v74, v29 quad_perm:[1,0,3,2] row_mask:0xf bank_mask:0xf
	v_mov_b32_dpp v75, v28 quad_perm:[1,0,3,2] row_mask:0xf bank_mask:0xf
	v_cndmask_b32_e64 v26, v26, v72, s[36:37]
	v_cndmask_b32_e64 v27, v73, v27, s[36:37]
	v_cndmask_b32_e64 v28, v28, v74, s[36:37]
	v_cndmask_b32_e64 v29, v75, v29, s[36:37]
	s_nop 1
	v_mov_b32_dpp v74, v26 quad_perm:[2,3,0,1] row_mask:0xf bank_mask:0xf
	v_mov_b32_dpp v75, v27 quad_perm:[2,3,0,1] row_mask:0xf bank_mask:0xf
	v_mov_b32_dpp v72, v28 quad_perm:[2,3,0,1] row_mask:0xf bank_mask:0xf
	v_mov_b32_dpp v73, v29 quad_perm:[2,3,0,1] row_mask:0xf bank_mask:0xf
	v_cndmask_b32_e64 v26, v26, v72, s[50:51]
	v_cndmask_b32_e64 v27, v27, v73, s[50:51]
	v_cndmask_b32_e64 v28, v74, v28, s[50:51]
	v_cndmask_b32_e64 v29, v75, v29, s[50:51]
	s_nop 1
	v_mov_b32_dpp v72, v23 quad_perm:[1,0,3,2] row_mask:0xf bank_mask:0xf
	v_mov_b32_dpp v73, v22 quad_perm:[1,0,3,2] row_mask:0xf bank_mask:0xf
	v_mov_b32_dpp v74, v25 quad_perm:[1,0,3,2] row_mask:0xf bank_mask:0xf
	v_mov_b32_dpp v75, v24 quad_perm:[1,0,3,2] row_mask:0xf bank_mask:0xf
	v_cndmask_b32_e64 v22, v22, v72, s[36:37]
	v_cndmask_b32_e64 v23, v73, v23, s[36:37]
	v_cndmask_b32_e64 v24, v24, v74, s[36:37]
	v_cndmask_b32_e64 v25, v75, v25, s[36:37]
	s_nop 1
	v_mov_b32_dpp v74, v22 quad_perm:[2,3,0,1] row_mask:0xf bank_mask:0xf
	v_mov_b32_dpp v75, v23 quad_perm:[2,3,0,1] row_mask:0xf bank_mask:0xf
	v_mov_b32_dpp v72, v24 quad_perm:[2,3,0,1] row_mask:0xf bank_mask:0xf
	v_mov_b32_dpp v73, v25 quad_perm:[2,3,0,1] row_mask:0xf bank_mask:0xf
	v_cndmask_b32_e64 v22, v22, v72, s[50:51]
	v_cndmask_b32_e64 v23, v23, v73, s[50:51]
	v_cndmask_b32_e64 v24, v74, v24, s[50:51]
	v_cndmask_b32_e64 v25, v75, v25, s[50:51]
	s_nop 1
	v_mov_b32_dpp v72, v19 quad_perm:[1,0,3,2] row_mask:0xf bank_mask:0xf
	v_mov_b32_dpp v73, v18 quad_perm:[1,0,3,2] row_mask:0xf bank_mask:0xf
	v_mov_b32_dpp v74, v21 quad_perm:[1,0,3,2] row_mask:0xf bank_mask:0xf
	v_mov_b32_dpp v75, v20 quad_perm:[1,0,3,2] row_mask:0xf bank_mask:0xf
	v_cndmask_b32_e64 v18, v18, v72, s[36:37]
	v_cndmask_b32_e64 v19, v73, v19, s[36:37]
	v_cndmask_b32_e64 v20, v20, v74, s[36:37]
	v_cndmask_b32_e64 v21, v75, v21, s[36:37]
	s_nop 1
	v_mov_b32_dpp v74, v18 quad_perm:[2,3,0,1] row_mask:0xf bank_mask:0xf
	v_mov_b32_dpp v75, v19 quad_perm:[2,3,0,1] row_mask:0xf bank_mask:0xf
	v_mov_b32_dpp v72, v20 quad_perm:[2,3,0,1] row_mask:0xf bank_mask:0xf
	v_mov_b32_dpp v73, v21 quad_perm:[2,3,0,1] row_mask:0xf bank_mask:0xf
	v_cndmask_b32_e64 v18, v18, v72, s[50:51]
	v_cndmask_b32_e64 v19, v19, v73, s[50:51]
	v_cndmask_b32_e64 v20, v74, v20, s[50:51]
	v_cndmask_b32_e64 v21, v75, v21, s[50:51]
	s_nop 1
	v_mov_b32_dpp v72, v15 quad_perm:[1,0,3,2] row_mask:0xf bank_mask:0xf
	v_mov_b32_dpp v73, v14 quad_perm:[1,0,3,2] row_mask:0xf bank_mask:0xf
	v_mov_b32_dpp v74, v17 quad_perm:[1,0,3,2] row_mask:0xf bank_mask:0xf
	v_mov_b32_dpp v75, v16 quad_perm:[1,0,3,2] row_mask:0xf bank_mask:0xf
	v_cndmask_b32_e64 v14, v14, v72, s[36:37]
	v_cndmask_b32_e64 v15, v73, v15, s[36:37]
	v_cndmask_b32_e64 v16, v16, v74, s[36:37]
	v_cndmask_b32_e64 v17, v75, v17, s[36:37]
	s_nop 1
	v_mov_b32_dpp v74, v14 quad_perm:[2,3,0,1] row_mask:0xf bank_mask:0xf
	v_mov_b32_dpp v75, v15 quad_perm:[2,3,0,1] row_mask:0xf bank_mask:0xf
	v_mov_b32_dpp v72, v16 quad_perm:[2,3,0,1] row_mask:0xf bank_mask:0xf
	v_mov_b32_dpp v73, v17 quad_perm:[2,3,0,1] row_mask:0xf bank_mask:0xf
	v_cndmask_b32_e64 v14, v14, v72, s[50:51]
	v_cndmask_b32_e64 v15, v15, v73, s[50:51]
	v_cndmask_b32_e64 v16, v74, v16, s[50:51]
	v_cndmask_b32_e64 v17, v75, v17, s[50:51]
	s_nop 1
	v_mov_b32_dpp v72, v11 quad_perm:[1,0,3,2] row_mask:0xf bank_mask:0xf
	v_mov_b32_dpp v73, v10 quad_perm:[1,0,3,2] row_mask:0xf bank_mask:0xf
	v_mov_b32_dpp v74, v13 quad_perm:[1,0,3,2] row_mask:0xf bank_mask:0xf
	v_mov_b32_dpp v75, v12 quad_perm:[1,0,3,2] row_mask:0xf bank_mask:0xf
	v_cndmask_b32_e64 v10, v10, v72, s[36:37]
	v_cndmask_b32_e64 v11, v73, v11, s[36:37]
	v_cndmask_b32_e64 v12, v12, v74, s[36:37]
	v_cndmask_b32_e64 v13, v75, v13, s[36:37]
	s_nop 1
	v_mov_b32_dpp v74, v10 quad_perm:[2,3,0,1] row_mask:0xf bank_mask:0xf
	v_mov_b32_dpp v75, v11 quad_perm:[2,3,0,1] row_mask:0xf bank_mask:0xf
	v_mov_b32_dpp v72, v12 quad_perm:[2,3,0,1] row_mask:0xf bank_mask:0xf
	v_mov_b32_dpp v73, v13 quad_perm:[2,3,0,1] row_mask:0xf bank_mask:0xf
	v_cndmask_b32_e64 v10, v10, v72, s[50:51]
	v_cndmask_b32_e64 v11, v11, v73, s[50:51]
	v_cndmask_b32_e64 v12, v74, v12, s[50:51]
	v_cndmask_b32_e64 v13, v75, v13, s[50:51]
	s_nop 1
	v_mov_b32_dpp v72, v7 quad_perm:[1,0,3,2] row_mask:0xf bank_mask:0xf
	v_mov_b32_dpp v73, v6 quad_perm:[1,0,3,2] row_mask:0xf bank_mask:0xf
	v_mov_b32_dpp v74, v9 quad_perm:[1,0,3,2] row_mask:0xf bank_mask:0xf
	v_mov_b32_dpp v75, v8 quad_perm:[1,0,3,2] row_mask:0xf bank_mask:0xf
	v_cndmask_b32_e64 v6, v6, v72, s[36:37]
	v_cndmask_b32_e64 v7, v73, v7, s[36:37]
	v_cndmask_b32_e64 v8, v8, v74, s[36:37]
	v_cndmask_b32_e64 v9, v75, v9, s[36:37]
	s_nop 1
	v_mov_b32_dpp v74, v6 quad_perm:[2,3,0,1] row_mask:0xf bank_mask:0xf
	v_mov_b32_dpp v75, v7 quad_perm:[2,3,0,1] row_mask:0xf bank_mask:0xf
	v_mov_b32_dpp v72, v8 quad_perm:[2,3,0,1] row_mask:0xf bank_mask:0xf
	v_mov_b32_dpp v73, v9 quad_perm:[2,3,0,1] row_mask:0xf bank_mask:0xf
	v_cndmask_b32_e64 v6, v6, v72, s[50:51]
	v_cndmask_b32_e64 v7, v7, v73, s[50:51]
	v_cndmask_b32_e64 v8, v74, v8, s[50:51]
	v_cndmask_b32_e64 v9, v75, v9, s[50:51]
	s_nop 1
	v_mov_b32_dpp v72, v3 quad_perm:[1,0,3,2] row_mask:0xf bank_mask:0xf
	v_mov_b32_dpp v73, v2 quad_perm:[1,0,3,2] row_mask:0xf bank_mask:0xf
	v_mov_b32_dpp v74, v5 quad_perm:[1,0,3,2] row_mask:0xf bank_mask:0xf
	v_mov_b32_dpp v75, v4 quad_perm:[1,0,3,2] row_mask:0xf bank_mask:0xf
	v_cndmask_b32_e64 v2, v2, v72, s[36:37]
	v_cndmask_b32_e64 v3, v73, v3, s[36:37]
	v_cndmask_b32_e64 v4, v4, v74, s[36:37]
	v_cndmask_b32_e64 v5, v75, v5, s[36:37]
	s_nop 1
	v_mov_b32_dpp v74, v2 quad_perm:[2,3,0,1] row_mask:0xf bank_mask:0xf
	v_mov_b32_dpp v75, v3 quad_perm:[2,3,0,1] row_mask:0xf bank_mask:0xf
	v_mov_b32_dpp v72, v4 quad_perm:[2,3,0,1] row_mask:0xf bank_mask:0xf
	v_mov_b32_dpp v73, v5 quad_perm:[2,3,0,1] row_mask:0xf bank_mask:0xf
	v_cndmask_b32_e64 v2, v2, v72, s[50:51]
	v_cndmask_b32_e64 v3, v3, v73, s[50:51]
	v_cndmask_b32_e64 v4, v74, v4, s[50:51]
	v_cndmask_b32_e64 v5, v75, v5, s[50:51]
	s_waitcnt lgkmcnt(0)
	v_cvt_pk_bf16_f32 v30, v30, v31
	v_cvt_pk_bf16_f32 v31, v32, v33
	ds_write_b64 v209, v[30:31] offset:0
	v_cvt_pk_bf16_f32 v26, v26, v27
	v_cvt_pk_bf16_f32 v27, v28, v29
	ds_write_b64 v210, v[26:27] offset:0
	v_cvt_pk_bf16_f32 v22, v22, v23
	v_cvt_pk_bf16_f32 v23, v24, v25
	ds_write_b64 v211, v[22:23] offset:0
	v_cvt_pk_bf16_f32 v18, v18, v19
	v_cvt_pk_bf16_f32 v19, v20, v21
	ds_write_b64 v212, v[18:19] offset:0
	v_cvt_pk_bf16_f32 v14, v14, v15
	v_cvt_pk_bf16_f32 v15, v16, v17
	ds_write_b64 v209, v[14:15] offset:2048
	v_cvt_pk_bf16_f32 v10, v10, v11
	v_cvt_pk_bf16_f32 v11, v12, v13
	ds_write_b64 v210, v[10:11] offset:2048
	v_cvt_pk_bf16_f32 v6, v6, v7
	v_cvt_pk_bf16_f32 v7, v8, v9
	ds_write_b64 v211, v[6:7] offset:2048
	v_cvt_pk_bf16_f32 v2, v2, v3
	v_cvt_pk_bf16_f32 v3, v4, v5
	ds_write_b64 v212, v[2:3] offset:2048
	s_waitcnt lgkmcnt(0)
	ds_read_b128 v[76:79], v213 offset:0
	ds_read_b128 v[80:83], v213 offset:1024
	ds_read_b128 v[84:87], v213 offset:2048
	ds_read_b128 v[88:91], v213 offset:3072
	s_waitcnt lgkmcnt(3)
	v_add_u32_e32 v216, 0x40000, v214
	global_store_dwordx4 v216, v[76:79], s[16:17] sc1
	s_waitcnt lgkmcnt(2)
	v_add_u32_e32 v216, 0x50000, v214
	global_store_dwordx4 v216, v[80:83], s[16:17] sc1
	s_waitcnt lgkmcnt(1)
	v_add_u32_e32 v216, 0x60000, v214
	global_store_dwordx4 v216, v[84:87], s[16:17] sc1
	s_waitcnt lgkmcnt(0)
	v_add_u32_e32 v216, 0x70000, v214
	global_store_dwordx4 v216, v[88:91], s[16:17] sc1
	s_nop 1
	s_and_b64 vcc, exec, s[34:35]
	s_cbranch_vccnz .Lrelu2_nost2
	s_mov_b64 s[16:17], 0x100
	s_mov_b64 s[36:37], 0x4100
	s_mov_b64 s[38:39], 0x8100
	v_lshl_add_u64 v[70:71], v[66:67], 0, s[16:17]
	s_add_i32 m0, s8, 0x18000
	s_nop 0
	global_load_lds_dwordx4 v[70:71], off
	v_lshl_add_u64 v[70:71], v[66:67], 0, s[36:37]
	s_mov_b32 m0, s45
	s_nop 0
	global_load_lds_dwordx4 v[70:71], off
	v_lshl_add_u64 v[70:71], v[66:67], 0, s[38:39]
	s_mov_b32 m0, s46
	s_mov_b64 s[38:39], 0xc100
	global_load_lds_dwordx4 v[70:71], off
	v_lshl_add_u64 v[66:67], v[66:67], 0, s[38:39]
	s_mov_b32 m0, s47
	s_nop 0
	global_load_lds_dwordx4 v[66:67], off
	v_lshl_add_u64 v[66:67], v[68:69], 0, s[16:17]
	s_add_i32 m0, s9, 0x20000
	s_nop 0
	global_load_lds_dwordx4 v[66:67], off
	v_lshl_add_u64 v[66:67], v[68:69], 0, s[36:37]
	s_mov_b32 m0, s48
	s_nop 0
	global_load_lds_dwordx4 v[66:67], off
.Lrelu2_nost2:
	s_mov_b64 s[38:39], -1
	s_and_b64 vcc, exec, s[34:35]
	s_cbranch_vccnz .LBB0_89
.LBB0_81:
	s_mul_hi_i32 s6, s49, 0x2aaaaaab
	s_lshr_b32 s14, s6, 31
	s_ashr_i32 s6, s6, 2
	s_add_i32 s6, s6, s14
	s_mul_i32 s14, s6, 24
	s_sub_i32 s14, s49, s14
	s_lshl_b32 s26, s14, 8
	s_lshl_b32 s22, s6, 7
	s_ashr_i32 s27, s26, 31
	s_ashr_i32 s23, s22, 31
	s_lshl_b64 s[34:35], s[26:27], 11
	s_lshl_b64 s[36:37], s[22:23], 11
	s_and_b64 vcc, exec, s[38:39]
	s_cbranch_vccnz .Lrelu2_pf
	s_mov_b32 m0, s8
	v_lshl_add_u64 v[2:3], v[102:103], 0, s[34:35]
	global_load_lds_dwordx4 v[2:3], off
	v_lshl_add_u64 v[6:7], v[2:3], 0, s[30:31]
	s_mov_b32 m0, s11
	s_mov_b64 s[16:17], 0xc000
	global_load_lds_dwordx4 v[6:7], off
	v_lshl_add_u64 v[6:7], v[2:3], 0, s[24:25]
	s_add_i32 m0, s8, 0x800
	v_lshl_add_u64 v[4:5], v[106:107], 0, s[36:37]
	global_load_lds_dwordx4 v[6:7], off
	v_lshl_add_u64 v[6:7], v[2:3], 0, s[16:17]
	s_mov_b32 m0, s12
	s_mov_b64 s[16:17], 0x4080
	global_load_lds_dwordx4 v[6:7], off
	s_mov_b32 m0, s13
	v_lshl_add_u64 v[6:7], v[4:5], 0, s[30:31]
	global_load_lds_dwordx4 v[4:5], off
	s_mov_b32 m0, s40
	s_mov_b64 s[38:39], 0x8080
	global_load_lds_dwordx4 v[6:7], off
	v_lshl_add_u64 v[6:7], v[2:3], 0, s[2:3]
	s_add_i32 m0, s8, 0xc000
	s_mov_b64 s[50:51], 0x8100
	global_load_lds_dwordx4 v[6:7], off
	v_lshl_add_u64 v[6:7], v[2:3], 0, s[16:17]
	s_mov_b32 m0, s41
	s_nop 0
	global_load_lds_dwordx4 v[6:7], off
	v_lshl_add_u64 v[6:7], v[2:3], 0, s[38:39]
	s_mov_b32 m0, s42
	s_mov_b64 s[38:39], 0xc080
	global_load_lds_dwordx4 v[6:7], off
	v_lshl_add_u64 v[6:7], v[2:3], 0, s[38:39]
	s_mov_b32 m0, s43
	s_mov_b64 s[38:39], 0x4100
	global_load_lds_dwordx4 v[6:7], off
	v_lshl_add_u64 v[6:7], v[4:5], 0, s[2:3]
	s_add_i32 m0, s9, 0x14000
	s_nop 0
	global_load_lds_dwordx4 v[6:7], off
	v_lshl_add_u64 v[6:7], v[4:5], 0, s[16:17]
	s_mov_b32 m0, s44
	s_mov_b64 s[16:17], 0x100
	global_load_lds_dwordx4 v[6:7], off
	v_lshl_add_u64 v[6:7], v[2:3], 0, s[16:17]
	s_add_i32 m0, s8, 0x18000
	s_nop 0
	global_load_lds_dwordx4 v[6:7], off
	v_lshl_add_u64 v[6:7], v[2:3], 0, s[38:39]
	s_mov_b32 m0, s45
	s_nop 0
	global_load_lds_dwordx4 v[6:7], off
	v_lshl_add_u64 v[6:7], v[2:3], 0, s[50:51]
	s_mov_b32 m0, s46
	s_mov_b64 s[50:51], 0xc100
	global_load_lds_dwordx4 v[6:7], off
	v_lshl_add_u64 v[2:3], v[2:3], 0, s[50:51]
	s_mov_b32 m0, s47
	s_nop 0
	global_load_lds_dwordx4 v[2:3], off
	v_lshl_add_u64 v[2:3], v[4:5], 0, s[16:17]
	s_add_i32 m0, s9, 0x20000
	s_nop 0
	global_load_lds_dwordx4 v[2:3], off
	v_lshl_add_u64 v[2:3], v[4:5], 0, s[38:39]
	s_mov_b32 m0, s48
	s_nop 0
	global_load_lds_dwordx4 v[2:3], off
	s_branch .LBB0_83
.Lrelu2_pf:
	s_waitcnt vmcnt(20)
	s_branch .Lrelu2_go

.Lrelu2_go:
	s_waitcnt lgkmcnt(0)
	s_barrier
	ds_read_b128 v[30:33], v133
	ds_read_b128 v[26:29], v134 offset:2048
	ds_read_b128 v[14:17], v134 offset:4096
	ds_read_b128 v[2:5], v134 offset:6144
	ds_read_b128 v[22:25], v135 offset:32768
	ds_read_b128 v[18:21], v161 offset:34816
	ds_read_b128 v[10:13], v161 offset:36864
	ds_read_b128 v[6:9], v161 offset:38912
	v_mov_b32_e32 v34, 0
	v_lshl_add_u64 v[116:117], v[112:113], 0, s[34:35]
	v_lshl_add_u64 v[118:119], v[114:115], 0, s[36:37]
	s_mov_b32 s6, -1
	s_mov_b32 s14, 0
	s_mov_b32 s19, 1
	s_mov_b32 s27, 0
	v_mov_b32_e32 v35, v34
	v_mov_b32_e32 v36, v34
	v_mov_b32_e32 v37, v34
	v_mov_b32_e32 v42, v34
	v_mov_b32_e32 v43, v34
	v_mov_b32_e32 v44, v34
	v_mov_b32_e32 v45, v34
	v_mov_b32_e32 v46, v34
	v_mov_b32_e32 v47, v34
	v_mov_b32_e32 v48, v34
	v_mov_b32_e32 v49, v34
	v_mov_b32_e32 v50, v34
	v_mov_b32_e32 v51, v34
	v_mov_b32_e32 v52, v34
	v_mov_b32_e32 v53, v34
	v_mov_b32_e32 v54, v34
	v_mov_b32_e32 v55, v34
	v_mov_b32_e32 v56, v34
	v_mov_b32_e32 v57, v34
	v_mov_b32_e32 v58, v34
	v_mov_b32_e32 v59, v34
	v_mov_b32_e32 v60, v34
	v_mov_b32_e32 v61, v34
	v_mov_b32_e32 v62, v34
	v_mov_b32_e32 v63, v34
	v_mov_b32_e32 v64, v34
	v_mov_b32_e32 v65, v34
	v_mov_b32_e32 v66, v34
	v_mov_b32_e32 v67, v34
	v_mov_b32_e32 v68, v34
	v_mov_b32_e32 v69, v34
	v_mov_b32_e32 v70, v34
	v_mov_b32_e32 v71, v34
	v_mov_b32_e32 v72, v34
	v_mov_b32_e32 v73, v34
	v_mov_b32_e32 v74, v34
	v_mov_b32_e32 v75, v34
	v_mov_b32_e32 v76, v34
	v_mov_b32_e32 v77, v34
	v_mov_b32_e32 v78, v34
	v_mov_b32_e32 v79, v34
	v_mov_b32_e32 v80, v34
	v_mov_b32_e32 v81, v34
	v_mov_b32_e32 v82, v34
	v_mov_b32_e32 v83, v34
	v_mov_b32_e32 v84, v34
	v_mov_b32_e32 v85, v34
	v_mov_b32_e32 v94, v34
	v_mov_b32_e32 v95, v34
	v_mov_b32_e32 v96, v34
	v_mov_b32_e32 v97, v34
	v_mov_b32_e32 v86, v34
	v_mov_b32_e32 v87, v34
	v_mov_b32_e32 v88, v34
	v_mov_b32_e32 v89, v34
	v_mov_b32_e32 v90, v34
	v_mov_b32_e32 v91, v34
	v_mov_b32_e32 v92, v34
	v_mov_b32_e32 v93, v34
	v_mov_b32_e32 v38, v34
	v_mov_b32_e32 v39, v34
	v_mov_b32_e32 v40, v34
	v_mov_b32_e32 v41, v34
.LBB0_84:
	s_mul_hi_u32 s34, s27, 0xaaaaaaab
	s_lshr_b32 s34, s34, 1
	s_mul_i32 s34, s34, 0x24000
	s_waitcnt lgkmcnt(0)
	v_mfma_f32_16x16x32_bf16 v[82:85], v[26:29], v[22:25], v[82:85]
	v_add_u32_e32 v191, s14, v99
	s_mul_hi_u32 s35, s19, 0xaaaaaaab
	s_lshr_b32 s35, s35, 1
	v_mfma_f32_16x16x32_bf16 v[78:81], v[26:29], v[18:21], v[78:81]
	s_mul_i32 s35, s35, 0x24000
	v_subrev_u32_e32 v180, s35, v128
	v_subrev_u32_e32 v181, s35, v129
	v_mfma_f32_16x16x32_bf16 v[74:77], v[26:29], v[10:13], v[74:77]
	v_subrev_u32_e32 v182, s35, v130
	v_mfma_f32_16x16x32_bf16 v[70:73], v[26:29], v[6:9], v[70:73]
	v_subrev_u32_e32 v26, s34, v127
	v_mfma_f32_16x16x32_bf16 v[66:69], v[14:17], v[22:25], v[66:69]
	v_mfma_f32_16x16x32_bf16 v[62:65], v[14:17], v[18:21], v[62:65]
	v_mfma_f32_16x16x32_bf16 v[58:61], v[14:17], v[10:13], v[58:61]
	v_mfma_f32_16x16x32_bf16 v[54:57], v[14:17], v[6:9], v[54:57]
	v_subrev_u32_e32 v14, s34, v131
	v_add_u32_e32 v16, v191, v26
	v_add_u32_e32 v14, v191, v14
	v_mfma_f32_16x16x32_bf16 v[38:41], v[30:33], v[22:25], v[38:41]
	v_subrev_u32_e32 v15, s35, v132
	v_mfma_f32_16x16x32_bf16 v[50:53], v[2:5], v[22:25], v[50:53]
	ds_read_b128 v[22:25], v16
	ds_read_b128 v[176:179], v16 offset:2048
	ds_read_b128 v[202:205], v16 offset:4096
	ds_read_b128 v[206:209], v16 offset:6144
	ds_read_b128 v[210:213], v14 offset:32768
	ds_read_b128 v[214:217], v14 offset:34816
	ds_read_b128 v[218:221], v14 offset:36864
	ds_read_b128 v[222:225], v14 offset:38912
	v_mfma_f32_16x16x32_bf16 v[90:93], v[30:33], v[18:21], v[90:93]
	v_mfma_f32_16x16x32_bf16 v[86:89], v[30:33], v[10:13], v[86:89]
	v_mfma_f32_16x16x32_bf16 v[94:97], v[30:33], v[6:9], v[94:97]
	v_mfma_f32_16x16x32_bf16 v[46:49], v[2:5], v[18:21], v[46:49]
	v_mfma_f32_16x16x32_bf16 v[42:45], v[2:5], v[10:13], v[42:45]
	v_mfma_f32_16x16x32_bf16 v[34:37], v[2:5], v[6:9], v[34:37]
	s_add_i32 s34, s6, 4
	s_mul_i32 s35, s34, 0xab
	s_bfe_u32 s35, s35, 0x70009
	s_mul_i32 s35, s35, 3
	s_sub_i32 s34, s34, s35
	s_and_b32 s34, s34, 0xff
	s_mul_i32 s36, s34, 0xc000
	s_waitcnt vmcnt(6)
	v_add_u32_e32 v2, v191, v15
	v_add_u32_e32 v6, v191, v182
	s_waitcnt lgkmcnt(0)
	v_mfma_f32_16x16x32_bf16 v[82:85], v[176:179], v[210:213], v[82:85]
	s_add_i32 s34, s36, s8
	s_waitcnt lgkmcnt(0)
	s_barrier
	v_mfma_f32_16x16x32_bf16 v[78:81], v[176:179], v[214:217], v[78:81]
	ds_read_b128 v[30:33], v2
	ds_read_b128 v[26:29], v2 offset:2048
	ds_read_b128 v[14:17], v2 offset:4096
	ds_read_b128 v[2:5], v2 offset:6144
	v_add_u32_e32 v7, v191, v181
	v_mfma_f32_16x16x32_bf16 v[74:77], v[176:179], v[218:221], v[74:77]
	s_mov_b32 m0, s34
	s_add_i32 s36, s36, s9
	s_add_i32 s27, s27, 1
	v_mfma_f32_16x16x32_bf16 v[70:73], v[176:179], v[222:225], v[70:73]
	v_lshl_add_u64 v[176:177], v[116:117], 0, v[100:101]
	v_lshl_add_u64 v[178:179], v[176:177], 0, s[84:85]
	v_mfma_f32_16x16x32_bf16 v[38:41], v[22:25], v[210:213], v[38:41]
	v_mfma_f32_16x16x32_bf16 v[90:93], v[22:25], v[214:217], v[90:93]
	v_mfma_f32_16x16x32_bf16 v[86:89], v[22:25], v[218:221], v[86:89]
	v_mfma_f32_16x16x32_bf16 v[94:97], v[22:25], v[222:225], v[94:97]
	ds_read_b128 v[22:25], v6
	ds_read_b128 v[18:21], v7
	v_add_u32_e32 v6, v191, v180
	ds_read_b128 v[10:13], v6
	ds_read_b128 v[6:9], v6 offset:2048
	global_load_lds_dwordx4 v[178:179], off
	v_lshl_add_u64 v[178:179], v[176:177], 0, s[76:77]
	s_add_i32 m0, s34, 0x400
	v_mfma_f32_16x16x32_bf16 v[66:69], v[202:205], v[210:213], v[66:69]
	global_load_lds_dwordx4 v[178:179], off
	v_lshl_add_u64 v[178:179], v[176:177], 0, s[54:55]
	s_add_i32 m0, s34, 0x800
	v_lshl_add_u64 v[176:177], v[176:177], 0, s[68:69]
	global_load_lds_dwordx4 v[178:179], off
	s_add_i32 m0, s34, 0xc00
	s_mov_b64 s[34:35], 0x2300180
	global_load_lds_dwordx4 v[176:177], off
	v_lshl_add_u64 v[176:177], v[118:119], 0, v[100:101]
	v_lshl_add_u64 v[178:179], v[176:177], 0, s[34:35]
	s_add_i32 m0, s36, 0x8000
	s_mov_b64 s[34:35], 0x2304180
	global_load_lds_dwordx4 v[178:179], off
	v_lshl_add_u64 v[176:177], v[176:177], 0, s[34:35]
	s_add_i32 m0, s36, 0x8400
	v_mfma_f32_16x16x32_bf16 v[62:65], v[202:205], v[214:217], v[62:65]
	global_load_lds_dwordx4 v[176:177], off
	v_mfma_f32_16x16x32_bf16 v[58:61], v[202:205], v[218:221], v[58:61]
	v_mfma_f32_16x16x32_bf16 v[54:57], v[202:205], v[222:225], v[54:57]
	v_mfma_f32_16x16x32_bf16 v[50:53], v[206:209], v[210:213], v[50:53]
	v_mfma_f32_16x16x32_bf16 v[46:49], v[206:209], v[214:217], v[46:49]
	v_mfma_f32_16x16x32_bf16 v[42:45], v[206:209], v[218:221], v[42:45]
	v_mfma_f32_16x16x32_bf16 v[34:37], v[206:209], v[222:225], v[34:37]
	s_add_i32 s6, s6, 1
	s_add_i32 s14, s14, 0xc000
	s_add_i32 s19, s19, 1
	v_lshl_add_u64 v[116:117], v[116:117], 0, s[2:3]
	s_cmp_eq_u32 s14, 0x9c000
	v_lshl_add_u64 v[118:119], v[118:119], 0, s[2:3]
	s_cbranch_scc0 .LBB0_84
	s_waitcnt lgkmcnt(0)
	v_mfma_f32_16x16x32_bf16 v[38:41], v[30:33], v[22:25], v[38:41]
	v_mfma_f32_16x16x32_bf16 v[90:93], v[30:33], v[18:21], v[90:93]
	v_mfma_f32_16x16x32_bf16 v[86:89], v[30:33], v[10:13], v[86:89]
	v_mfma_f32_16x16x32_bf16 v[30:33], v[30:33], v[6:9], v[94:97]
	v_mfma_f32_16x16x32_bf16 v[82:85], v[26:29], v[22:25], v[82:85]
	v_mfma_f32_16x16x32_bf16 v[78:81], v[26:29], v[18:21], v[78:81]
	v_mfma_f32_16x16x32_bf16 v[74:77], v[26:29], v[10:13], v[74:77]
	v_mfma_f32_16x16x32_bf16 v[26:29], v[26:29], v[6:9], v[70:73]
	v_mfma_f32_16x16x32_bf16 v[66:69], v[14:17], v[22:25], v[66:69]
	v_mfma_f32_16x16x32_bf16 v[62:65], v[14:17], v[18:21], v[62:65]
	v_mfma_f32_16x16x32_bf16 v[58:61], v[14:17], v[10:13], v[58:61]
	v_mfma_f32_16x16x32_bf16 v[14:17], v[14:17], v[6:9], v[54:57]
	v_mfma_f32_16x16x32_bf16 v[22:25], v[2:5], v[22:25], v[50:53]
	v_mfma_f32_16x16x32_bf16 v[18:21], v[2:5], v[18:21], v[46:49]
	s_nop 2
	ds_read_b128 v[46:49], v163
	ds_read_b128 v[50:53], v164 offset:2048
	ds_read_b128 v[54:57], v164 offset:4096
	ds_read_b128 v[70:73], v164 offset:6144
	v_mfma_f32_16x16x32_bf16 v[10:13], v[2:5], v[10:13], v[42:45]
	s_nop 2
	ds_read_b128 v[42:45], v165 offset:32768
	ds_read_b128 v[94:97], v166 offset:34816
	ds_read_b128 v[116:119], v166 offset:36864
	ds_read_b128 v[176:179], v166 offset:38912
	v_mfma_f32_16x16x32_bf16 v[2:5], v[2:5], v[6:9], v[34:37]
	s_waitcnt lgkmcnt(0)
	v_mfma_f32_16x16x32_bf16 v[6:9], v[46:49], v[42:45], v[38:41]
	s_waitcnt vmcnt(6)
	s_waitcnt lgkmcnt(0)
	s_barrier
	v_mfma_f32_16x16x32_bf16 v[34:37], v[46:49], v[94:97], v[90:93]
	v_mfma_f32_16x16x32_bf16 v[38:41], v[46:49], v[116:119], v[86:89]
	s_nop 1
	v_add_u32_e32 v90, 0x20800, v161
	v_mfma_f32_16x16x32_bf16 v[30:33], v[46:49], v[176:179], v[30:33]
	v_mfma_f32_16x16x32_bf16 v[46:49], v[50:53], v[42:45], v[82:85]
	v_mfma_f32_16x16x32_bf16 v[78:81], v[50:53], v[94:97], v[78:81]
	v_mfma_f32_16x16x32_bf16 v[74:77], v[50:53], v[116:119], v[74:77]
	v_mfma_f32_16x16x32_bf16 v[26:29], v[50:53], v[176:179], v[26:29]
	v_mfma_f32_16x16x32_bf16 v[50:53], v[54:57], v[42:45], v[66:69]
	v_mfma_f32_16x16x32_bf16 v[62:65], v[54:57], v[94:97], v[62:65]
	v_mfma_f32_16x16x32_bf16 v[58:61], v[54:57], v[116:119], v[58:61]
	v_mfma_f32_16x16x32_bf16 v[14:17], v[54:57], v[176:179], v[14:17]
	v_add_u32_e32 v54, v126, v120
	ds_read_b128 v[54:57], v54
	ds_read_b128 v[66:69], v167 offset:2048
	v_mfma_f32_16x16x32_bf16 v[18:21], v[70:73], v[94:97], v[18:21]
	v_add_u32_e32 v94, 0x21000, v161
	v_mfma_f32_16x16x32_bf16 v[10:13], v[70:73], v[116:119], v[10:13]
	v_add_u32_e32 v116, 0x21800, v161
	v_mfma_f32_16x16x32_bf16 v[22:25], v[70:73], v[42:45], v[22:25]
	ds_read_b128 v[42:45], v167 offset:4096
	ds_read_b128 v[82:85], v167 offset:6144
	ds_read_b128 v[86:89], v168
	ds_read_b128 v[90:93], v90
	ds_read_b128 v[94:97], v94
	ds_read_b128 v[116:119], v116
	v_mfma_f32_16x16x32_bf16 v[2:5], v[70:73], v[176:179], v[2:5]
	s_waitcnt lgkmcnt(0)
	v_mfma_f32_16x16x32_bf16 v[50:53], v[42:45], v[86:89], v[50:53]
	v_mfma_f32_16x16x32_bf16 v[62:65], v[42:45], v[90:93], v[62:65]
	v_mfma_f32_16x16x32_bf16 v[58:61], v[42:45], v[94:97], v[58:61]
	v_mfma_f32_16x16x32_bf16 v[14:17], v[42:45], v[116:119], v[14:17]
	v_add_u32_e32 v42, v126, v124
	v_mfma_f32_16x16x32_bf16 v[6:9], v[54:57], v[86:89], v[6:9]
	v_mfma_f32_16x16x32_bf16 v[34:37], v[54:57], v[90:93], v[34:37]
	v_mfma_f32_16x16x32_bf16 v[38:41], v[54:57], v[94:97], v[38:41]
	v_mfma_f32_16x16x32_bf16 v[30:33], v[54:57], v[116:119], v[30:33]
	v_mfma_f32_16x16x32_bf16 v[46:49], v[66:69], v[86:89], v[46:49]
	v_mfma_f32_16x16x32_bf16 v[54:57], v[66:69], v[90:93], v[78:81]
	v_mfma_f32_16x16x32_bf16 v[70:73], v[66:69], v[94:97], v[74:77]
	v_mfma_f32_16x16x32_bf16 v[26:29], v[66:69], v[116:119], v[26:29]
	ds_read_b128 v[42:45], v42
	ds_read_b128 v[66:69], v169
	ds_read_b128 v[74:77], v170
	ds_read_b128 v[78:81], v171
	v_mfma_f32_16x16x32_bf16 v[22:25], v[82:85], v[86:89], v[22:25]
	v_mfma_f32_16x16x32_bf16 v[18:21], v[82:85], v[90:93], v[18:21]
	v_mfma_f32_16x16x32_bf16 v[10:13], v[82:85], v[94:97], v[10:13]
	ds_read_b128 v[86:89], v172
	ds_read_b128 v[90:93], v173
	ds_read_b128 v[94:97], v174
	ds_read_b128 v[176:179], v175
	v_mfma_f32_16x16x32_bf16 v[2:5], v[82:85], v[116:119], v[2:5]
	s_waitcnt vmcnt(0)
	s_waitcnt lgkmcnt(0)
	v_mfma_f32_16x16x32_bf16 v[6:9], v[42:45], v[86:89], v[6:9]
	s_waitcnt lgkmcnt(0)
	s_barrier
	v_mfma_f32_16x16x32_bf16 v[34:37], v[42:45], v[90:93], v[34:37]
	v_mfma_f32_16x16x32_bf16 v[38:41], v[42:45], v[94:97], v[38:41]
	v_mfma_f32_16x16x32_bf16 v[30:33], v[42:45], v[176:179], v[30:33]
	v_mfma_f32_16x16x32_bf16 v[42:45], v[66:69], v[86:89], v[46:49]
	v_mfma_f32_16x16x32_bf16 v[46:49], v[66:69], v[90:93], v[54:57]
	v_mfma_f32_16x16x32_bf16 v[54:57], v[66:69], v[94:97], v[70:73]
	v_mfma_f32_16x16x32_bf16 v[26:29], v[66:69], v[176:179], v[26:29]
	v_mfma_f32_16x16x32_bf16 v[50:53], v[74:77], v[86:89], v[50:53]
	v_mfma_f32_16x16x32_bf16 v[62:65], v[74:77], v[90:93], v[62:65]
	v_mfma_f32_16x16x32_bf16 v[58:61], v[74:77], v[94:97], v[58:61]
	v_mfma_f32_16x16x32_bf16 v[14:17], v[74:77], v[176:179], v[14:17]
	ds_read_b128 v[66:69], v161 offset:38912
	ds_read_b128 v[70:73], v161 offset:36864
	ds_read_b128 v[74:77], v161 offset:34816
	ds_read_b128 v[82:85], v135 offset:32768
	v_mfma_f32_16x16x32_bf16 v[22:25], v[78:81], v[86:89], v[22:25]
	v_mfma_f32_16x16x32_bf16 v[18:21], v[78:81], v[90:93], v[18:21]
	v_mfma_f32_16x16x32_bf16 v[10:13], v[78:81], v[94:97], v[10:13]
	ds_read_b128 v[86:89], v134 offset:6144
	ds_read_b128 v[90:93], v134 offset:4096
	ds_read_b128 v[94:97], v134 offset:2048
	ds_read_b128 v[116:119], v133
	v_mfma_f32_16x16x32_bf16 v[2:5], v[78:81], v[176:179], v[2:5]
	s_waitcnt lgkmcnt(0)
	v_mfma_f32_16x16x32_bf16 v[78:81], v[94:97], v[74:77], v[46:49]
	s_nop 2
	v_add_u32_e32 v46, v105, v124
	v_mfma_f32_16x16x32_bf16 v[6:9], v[116:119], v[82:85], v[6:9]
	v_add_u32_e32 v47, v121, v124
	v_mfma_f32_16x16x32_bf16 v[34:37], v[116:119], v[74:77], v[34:37]
	v_mfma_f32_16x16x32_bf16 v[38:41], v[116:119], v[70:73], v[38:41]
	v_mfma_f32_16x16x32_bf16 v[30:33], v[116:119], v[66:69], v[30:33]
	v_mfma_f32_16x16x32_bf16 v[42:45], v[94:97], v[82:85], v[42:45]
	v_mfma_f32_16x16x32_bf16 v[116:119], v[94:97], v[70:73], v[54:57]
	v_mfma_f32_16x16x32_bf16 v[26:29], v[94:97], v[66:69], v[26:29]
	v_mfma_f32_16x16x32_bf16 v[94:97], v[90:93], v[82:85], v[50:53]
	v_mfma_f32_16x16x32_bf16 v[176:179], v[90:93], v[74:77], v[62:65]
	v_mfma_f32_16x16x32_bf16 v[202:205], v[90:93], v[70:73], v[58:61]
	v_mfma_f32_16x16x32_bf16 v[14:17], v[90:93], v[66:69], v[14:17]
	v_mfma_f32_16x16x32_bf16 v[82:85], v[86:89], v[82:85], v[22:25]
	s_nop 2
	ds_read_b128 v[22:25], v46
	ds_read_b128 v[90:93], v47 offset:2048
	v_add_u32_e32 v46, v122, v124
	v_mfma_f32_16x16x32_bf16 v[74:77], v[86:89], v[74:77], v[18:21]
	s_nop 2
	ds_read_b128 v[18:21], v47 offset:4096
	ds_read_b128 v[206:209], v47 offset:6144
	v_add_u32_e32 v47, v123, v124
	v_mfma_f32_16x16x32_bf16 v[70:73], v[86:89], v[70:73], v[10:13]
	s_nop 2
	ds_read_b128 v[10:13], v46 offset:32768
	ds_read_b128 v[210:213], v47 offset:34816
	ds_read_b128 v[214:217], v47 offset:36864
	ds_read_b128 v[218:221], v47 offset:38912
	v_mfma_f32_16x16x32_bf16 v[2:5], v[86:89], v[66:69], v[2:5]
	s_waitcnt lgkmcnt(0)
	v_mfma_f32_16x16x32_bf16 v[62:65], v[22:25], v[10:13], v[6:9]
	s_waitcnt vmcnt(0)
	s_waitcnt lgkmcnt(0)
	s_barrier
	v_mfma_f32_16x16x32_bf16 v[58:61], v[22:25], v[210:213], v[34:37]
	v_mfma_f32_16x16x32_bf16 v[54:57], v[22:25], v[214:217], v[38:41]
	v_mfma_f32_16x16x32_bf16 v[50:53], v[22:25], v[218:221], v[30:33]
	v_mfma_f32_16x16x32_bf16 v[46:49], v[90:93], v[10:13], v[42:45]
	v_mfma_f32_16x16x32_bf16 v[42:45], v[90:93], v[210:213], v[78:81]
	v_mfma_f32_16x16x32_bf16 v[38:41], v[90:93], v[214:217], v[116:119]
	v_mfma_f32_16x16x32_bf16 v[34:37], v[90:93], v[218:221], v[26:29]
	v_mfma_f32_16x16x32_bf16 v[30:33], v[18:21], v[10:13], v[94:97]
	v_mfma_f32_16x16x32_bf16 v[26:29], v[18:21], v[210:213], v[176:179]
	v_mfma_f32_16x16x32_bf16 v[22:25], v[18:21], v[214:217], v[202:205]
	v_mfma_f32_16x16x32_bf16 v[18:21], v[18:21], v[218:221], v[14:17]
	v_mfma_f32_16x16x32_bf16 v[14:17], v[206:209], v[10:13], v[82:85]
	v_mfma_f32_16x16x32_bf16 v[10:13], v[206:209], v[210:213], v[74:77]
	v_mfma_f32_16x16x32_bf16 v[6:9], v[206:209], v[214:217], v[70:73]
	v_mfma_f32_16x16x32_bf16 v[2:5], v[206:209], v[218:221], v[2:5]
	s_waitcnt lgkmcnt(0)
	s_barrier
	s_load_dword s6, s[78:79], 0x0
	s_waitcnt lgkmcnt(0)
	s_add_i32 s49, s6, s49
	s_cmpk_gt_i32 s49, 0x2ff
	s_cselect_b64 s[34:35], -1, 0
	s_cmpk_lt_i32 s49, 0x300
	s_cbranch_scc0 .LBB0_80
	s_mul_hi_i32 s6, s49, 0x2aaaaaab
	s_lshr_b32 s14, s6, 31
	s_ashr_i32 s6, s6, 2
	s_add_i32 s6, s6, s14
	s_mul_i32 s14, s6, 24
	s_sub_i32 s14, s49, s14
	v_lshl_add_u32 v66, s14, 8, v98
	v_ashrrev_i32_e32 v67, 31, v66
	v_lshlrev_b64 v[66:67], 11, v[66:67]
	s_mov_b32 m0, s8
	v_lshl_add_u64 v[66:67], v[108:109], 0, v[66:67]
	v_lshl_add_u32 v68, s6, 7, v104
	global_load_lds_dwordx4 v[66:67], off
	v_lshl_add_u64 v[70:71], v[66:67], 0, s[30:31]
	s_mov_b32 m0, s11
	v_ashrrev_i32_e32 v69, 31, v68
	global_load_lds_dwordx4 v[70:71], off
	v_lshl_add_u64 v[70:71], v[66:67], 0, s[24:25]
	s_add_i32 m0, s8, 0x800
	s_mov_b64 s[16:17], 0xc000
	v_lshlrev_b64 v[68:69], 11, v[68:69]
	global_load_lds_dwordx4 v[70:71], off
	v_lshl_add_u64 v[70:71], v[66:67], 0, s[16:17]
	s_mov_b32 m0, s12
	v_lshl_add_u64 v[68:69], v[110:111], 0, v[68:69]
	global_load_lds_dwordx4 v[70:71], off
	s_mov_b32 m0, s13
	v_lshl_add_u64 v[70:71], v[68:69], 0, s[30:31]
	global_load_lds_dwordx4 v[68:69], off
	s_mov_b32 m0, s40
	s_mov_b64 s[16:17], 0x4080
	global_load_lds_dwordx4 v[70:71], off
	v_lshl_add_u64 v[70:71], v[66:67], 0, s[2:3]
	s_add_i32 m0, s8, 0xc000
	s_mov_b64 s[36:37], 0x8080
	global_load_lds_dwordx4 v[70:71], off
	v_lshl_add_u64 v[70:71], v[66:67], 0, s[16:17]
	s_mov_b32 m0, s41
	s_mov_b64 s[38:39], 0x8100
	global_load_lds_dwordx4 v[70:71], off
	v_lshl_add_u64 v[70:71], v[66:67], 0, s[36:37]
	s_mov_b32 m0, s42
	s_mov_b64 s[36:37], 0xc080
	global_load_lds_dwordx4 v[70:71], off
	v_lshl_add_u64 v[70:71], v[66:67], 0, s[36:37]
	s_mov_b32 m0, s43
	s_mov_b64 s[36:37], 0x4100
	global_load_lds_dwordx4 v[70:71], off
	v_lshl_add_u64 v[70:71], v[68:69], 0, s[2:3]
	s_add_i32 m0, s9, 0x14000
	s_nop 0
	global_load_lds_dwordx4 v[70:71], off
	v_lshl_add_u64 v[70:71], v[68:69], 0, s[16:17]
	s_mov_b32 m0, s44
	s_mov_b64 s[16:17], 0x100
	global_load_lds_dwordx4 v[70:71], off
	s_branch .LBB0_80
